# RG-LRU chunk chain: decoupled look-back (chunk composites published early; incoming state rebuilt from the previous round's state and the same-round composites, bit-identical arithmetic)
# baseline (speedup 1.0000x reference)
; __device__ __forceinline__ void p0_prologue(const Ptrs& P, LAS unsigned char* lds, int gw, int NGW, int wave, int lane, int gtid, int GT, int part) {
;     ...
;     float* ssq0 = (float*)(P.ws + WS_SSQ0); float* ssq1 = (float*)(P.ws + WS_SSQ1); float* ssq2 = (float*)(P.ws + WS_SSQ2);
;     for (int g = gtid; g < M; g += GT) { ssq1[g] = 0.0f; ssq2[g] = 0.0f; }
;     { unsigned long long* XS = (unsigned long long*)(P.ws + WS_X); for (int g = gtid; g < M * 4 + 1024; g += GT) XS[g] = 0ull; }
;     { unsigned long long* GR = (unsigned long long*)(P.ws + WS_SUM); for (int g = gtid; g < 64 * NCHUNK * LB; g += GT) GR[g] = 0ull; }
.Lp0_skip_tables:
	v_lshlrev_b32_e32 v177, 3, v232
	v_mov_b32_e32 v178, 0
	v_mov_b32_e32 v179, 0
	s_lshl_b32 s2, s60, 9
	s_lshl_b32 s3, s62, 9
.Lp0_zero_cd:
	s_cmp_ge_u32 s2, 0x100000
	s_cbranch_scc1 .Lp0_zero_cd_done
	s_add_u32 s4, s54, s2
	s_addc_u32 s5, s55, 0
	s_add_u32 s4, s4, 0x1300000
	s_addc_u32 s5, s5, 0
	global_store_dwordx2 v177, v[178:179], s[4:5]
	s_add_i32 s2, s2, s3
	s_branch .Lp0_zero_cd

; #define LAS __attribute__((address_space(3)))
; __device__ __forceinline__ unsigned pk2(float lo, float hi) { f32x2_t v = {lo, hi}; bf16x2_t b = __builtin_convertvector(v, bf16x2_t); return __builtin_bit_cast(unsigned, b); }
; __device__ __forceinline__ float bflo(unsigned u) { return __uint_as_float(u << 16); }
; __device__ __forceinline__ float bfhi(unsigned u) { return __uint_as_float(u & 0xffff0000u); }
; __device__ __forceinline__ float sigmoid_(float x) { return rcpf_(1.0f + ex2(-LOG2E * x)); }
; __device__ __forceinline__ void lru_phase(const Ptrs& P, LAS unsigned char* lds, int G, int wave, int lane, int tid) {
;     ...
;         { const LAS float* hp = (const LAS float*)(lds + L_HIN) + wave * 80 + 4 * hh;
;           bf16* yp = YG + trow * LW + hd * LB + 8 * hh;
; #pragma unroll
;           for (int s = 0; s < 5; ++s) { v2u pk[2];
; #pragma unroll
;               for (int half = 0; half < 2; ++half) { const int ch0 = 16 * s + 8 * half;
;                   const f32x4 hin = *(const LAS f32x4*)(hp + ch0); const v2u graw = graw_[s * 2 + half];
;                   const float g0 = bflo(graw.x), g1 = bfhi(graw.x), g2 = bflo(graw.y), g3 = bfhi(graw.y);
;                   const float y0 = (xc[s][half][0] + Av[s][half][0] * hin[0]) * (g0 * sigmoid_(g0));
;                   const float y1 = (xc[s][half][1] + Av[s][half][1] * hin[1]) * (g1 * sigmoid_(g1));
;                   const float y2 = (xc[s][half][2] + Av[s][half][2] * hin[2]) * (g2 * sigmoid_(g2));
;                   const float y3 = (xc[s][half][3] + Av[s][half][3] * hin[3]) * (g3 * sigmoid_(g3));
;                   pk[half].x = pk2(y0, y1); pk[half].y = pk2(y2, y3); }
;               const auto rx = __builtin_amdgcn_permlane32_swap(pk[0].x, pk[1].x, false, false), ry = __builtin_amdgcn_permlane32_swap(pk[0].y, pk[1].y, false, false);
;               const v4u o = {rx[0], ry[0], rx[1], ry[1]};
;               *(v4u*)(yp + 16 * s) = o; __builtin_amdgcn_sched_barrier(0); } }
.LBB0_304:
	s_or_b64 exec, exec, s[2:3]
	global_load_dwordx2 v[162:163], v[0:1], off offset:1024
	global_load_dwordx2 v[158:159], v[0:1], off offset:1536
	global_load_dwordx2 v[152:153], v[0:1], off offset:2048
	global_load_dwordx2 v[146:147], v[0:1], off offset:2560
	global_load_dwordx2 v[140:141], v[0:1], off offset:3072
	global_load_dwordx2 v[122:123], v[0:1], off offset:3584
	v_add_co_u32_e32 v2, vcc, s5, v0
	v_mov_b32_e32 v128, 0
	s_nop 0
	v_addc_co_u32_e32 v3, vcc, 0, v1, vcc
	global_load_dwordx2 v[174:175], v[0:1], off
	global_load_dwordx2 v[170:171], v[0:1], off offset:512
	global_load_dwordx2 v[120:121], v[2:3], off
	global_load_dwordx2 v[26:27], v[2:3], off offset:512
	v_mov_b32_e32 v0, 0x3f80
	v_cmp_gt_u32_e32 vcc, 32, v232
	v_mov_b32_e32 v1, v128
	s_mov_b64 s[2:3], 0x6000000
	v_cndmask_b32_e32 v32, 0, v0, vcc
	v_lshlrev_b32_e32 v0, 3, v232
	v_lshl_add_u64 v[0:1], s[54:55], 0, v[0:1]
	v_lshl_add_u64 v[130:131], v[0:1], 0, s[2:3]
	v_lshlrev_b32_e32 v0, 3, v184
	v_mov_b32_e32 v1, v128
	v_lshl_add_u64 v[0:1], s[54:55], 0, v[0:1]
	s_mov_b64 s[6:7], 0x130000
	s_add_u32 s16, s54, 0x8c00000
	v_lshrrev_b32_e32 v2, 5, v232
	s_mul_i32 s4, s63, 0x280
	v_lshl_add_u64 v[132:133], v[0:1], 0, s[6:7]
	v_and_or_b32 v1, v4, 31, v187
	s_addc_u32 s17, s55, 0
	v_lshlrev_b32_e32 v233, 4, v2
	s_add_i32 s27, s4, 0
	s_movk_i32 s4, 0x50
	s_mul_i32 s6, s63, 0xfffffec0
	v_lshlrev_b32_e32 v0, 3, v2
	v_lshlrev_b32_e32 v2, 3, v1
	v_mov_b32_e32 v3, v128
	v_add_u32_e32 v234, 0, v233
	v_mov_b32_e32 v33, v128
	v_mov_b32_e32 v34, v128
	v_mov_b32_e32 v35, v128
	v_cmp_eq_u32_e64 s[2:3], 31, v185
	v_add_u32_e32 v235, s26, v4
	v_cmp_gt_u32_e64 s[4:5], s4, v184
	v_lshl_add_u32 v236, v184, 2, 0
	s_add_i32 s28, s27, s6
	v_lshl_add_u32 v237, v232, 4, 0
	v_lshl_add_u64 v[134:135], s[10:11], 0, v[2:3]
	v_mov_b32_e32 v238, 0x3d2aaaab
	v_mov_b32_e32 v240, 1.0
	v_mov_b32_e32 v242, 0x3fb17218
	v_mov_b32_e32 v244, 0x3c088889
	v_mov_b32_e32 v246, 0x3e2aaaab
	v_mov_b32_e32 v248, 0.5
	s_mov_b32 s29, 0xbe800000
	s_mov_b32 s15, 1
	v_mov_b32_e32 v137, 1
	s_movk_i32 s30, 0xa00
	v_lshlrev_b32_e32 v138, 1, v0
	v_mov_b32_e32 v239, 0x280
	s_mov_b32 s20, s33
	s_branch .LBB0_308
.LBB0_307:
	s_or_b64 exec, exec, s[20:21]
	v_or_b32_e32 v198, s34, v185
	s_lshl_b32 s6, s31, 12
	v_ashrrev_i32_e32 v199, 31, v198
	s_mov_b32 s7, s14
	v_lshl_add_u64 v[198:199], v[198:199], 0, s[6:7]
	v_mov_b64_e32 v[202:203], s[16:17]
	v_mad_u64_u32 v[202:203], s[6:7], v198, s30, v[202:203]
	v_mad_i32_i24 v203, v199, s30, v203
	s_mul_i32 s6, s37, 0xa0
	s_mov_b32 s7, s14
	s_waitcnt vmcnt(49)
	v_lshlrev_b32_e32 v210, 16, v200
	v_lshl_add_u64 v[198:199], v[202:203], 0, s[6:7]
	v_mov_b32_e32 v139, v128
	v_add_u32_e32 v129, s28, v233
	v_mul_f32_e32 v136, 0xbfb8aa3b, v210
	v_and_b32_e32 v211, 0xffff0000, v200
	s_waitcnt lgkmcnt(0)
	s_barrier
	v_lshl_add_u64 v[198:199], v[198:199], 0, v[138:139]
	s_waitcnt vmcnt(0)
	ds_read_b128 v[202:205], v129 offset:44544
	ds_read_b128 v[206:209], v129 offset:44576
	v_exp_f32_e32 v136, v136
	v_mul_f32_e32 v139, 0xbfb8aa3b, v211
	v_exp_f32_e32 v139, v139
	s_waitcnt lgkmcnt(1)
	v_pk_fma_f32 v[44:45], v[44:45], v[202:203], v[48:49]
	v_add_f32_e32 v136, 1.0, v136
	v_lshlrev_b32_e32 v48, 16, v201
	v_rcp_f32_e32 v200, v136
	v_add_f32_e32 v136, 1.0, v139
	v_and_b32_e32 v49, 0xffff0000, v201
	v_mul_f32_e32 v139, 0xbfb8aa3b, v48
	v_exp_f32_e32 v139, v139
	v_mul_f32_e32 v201, 0xbfb8aa3b, v49
	v_exp_f32_e32 v203, v201
	v_rcp_f32_e32 v201, v136
	v_add_f32_e32 v136, 1.0, v139
	v_rcp_f32_e32 v202, v136
	v_add_f32_e32 v136, 1.0, v203
	v_rcp_f32_e32 v203, v136
	v_pk_mul_f32 v[200:201], v[200:201], v[210:211]
	v_pk_fma_f32 v[46:47], v[46:47], v[204:205], v[50:51]
	v_pk_mul_f32 v[44:45], v[200:201], v[44:45]
	v_pk_mul_f32 v[48:49], v[202:203], v[48:49]
	v_cvt_pk_bf16_f32 v44, v44, v45
	v_pk_mul_f32 v[46:47], v[48:49], v[46:47]
	s_waitcnt lgkmcnt(0)
	v_pk_fma_f32 v[50:51], v[52:53], v[206:207], v[56:57]
	v_cvt_pk_bf16_f32 v45, v46, v47
	v_lshlrev_b32_e32 v46, 16, v196
	v_mul_f32_e32 v47, 0xbfb8aa3b, v46
	v_exp_f32_e32 v48, v47
	v_and_b32_e32 v47, 0xffff0000, v196
	v_mul_f32_e32 v49, 0xbfb8aa3b, v47
	v_lshlrev_b32_e32 v52, 16, v197
	v_and_b32_e32 v53, 0xffff0000, v197
	v_exp_f32_e32 v49, v49
	v_mul_f32_e32 v56, 0xbfb8aa3b, v52
	v_mul_f32_e32 v57, 0xbfb8aa3b, v53
	v_exp_f32_e32 v56, v56
	v_exp_f32_e32 v57, v57
	v_add_f32_e32 v48, 1.0, v48
	v_add_f32_e32 v49, 1.0, v49
	v_rcp_f32_e32 v48, v48
	v_rcp_f32_e32 v49, v49
	v_add_f32_e32 v56, 1.0, v56
	v_add_f32_e32 v57, 1.0, v57
	v_rcp_f32_e32 v56, v56
	v_rcp_f32_e32 v57, v57
	v_pk_mul_f32 v[46:47], v[48:49], v[46:47]
	v_pk_fma_f32 v[48:49], v[54:55], v[208:209], v[58:59]
	v_pk_mul_f32 v[46:47], v[46:47], v[50:51]
	v_pk_mul_f32 v[50:51], v[56:57], v[52:53]
	v_cvt_pk_bf16_f32 v46, v46, v47
	v_pk_mul_f32 v[48:49], v[50:51], v[48:49]
	s_nop 0
	v_permlane32_swap_b32_e32 v44, v46
	v_cvt_pk_bf16_f32 v47, v48, v49
	s_nop 1
	v_permlane32_swap_b32_e32 v45, v47
	global_store_dwordx4 v[198:199], v[44:47], off
	v_lshlrev_b32_e32 v52, 16, v194
	v_mul_f32_e32 v53, 0xbfb8aa3b, v52
	v_exp_f32_e32 v54, v53
	v_and_b32_e32 v53, 0xffff0000, v194
	v_mul_f32_e32 v55, 0xbfb8aa3b, v53
	v_lshlrev_b32_e32 v56, 16, v195
	v_and_b32_e32 v57, 0xffff0000, v195
	v_exp_f32_e32 v55, v55
	v_mul_f32_e32 v58, 0xbfb8aa3b, v56
	v_mul_f32_e32 v59, 0xbfb8aa3b, v57
	v_exp_f32_e32 v58, v58
	v_exp_f32_e32 v59, v59
	v_add_f32_e32 v54, 1.0, v54
	v_add_f32_e32 v55, 1.0, v55
	ds_read_b128 v[44:47], v129 offset:44608
	ds_read_b128 v[48:51], v129 offset:44640
	v_rcp_f32_e32 v54, v54
	v_rcp_f32_e32 v55, v55
	v_add_f32_e32 v58, 1.0, v58
	v_add_f32_e32 v59, 1.0, v59
	v_rcp_f32_e32 v58, v58
	v_rcp_f32_e32 v59, v59
	s_waitcnt lgkmcnt(1)
; #define LAS __attribute__((address_space(3)))
; __device__ __forceinline__ unsigned pk2(float lo, float hi) { f32x2_t v = {lo, hi}; bf16x2_t b = __builtin_convertvector(v, bf16x2_t); return __builtin_bit_cast(unsigned, b); }
; __device__ __forceinline__ float bflo(unsigned u) { return __uint_as_float(u << 16); }
; __device__ __forceinline__ float bfhi(unsigned u) { return __uint_as_float(u & 0xffff0000u); }
; __device__ __forceinline__ float sigmoid_(float x) { return rcpf_(1.0f + ex2(-LOG2E * x)); }
; __device__ __forceinline__ void lru_phase(const Ptrs& P, LAS unsigned char* lds, int G, int wave, int lane, int tid) {
;     ...
;           for (int s = 0; s < 5; ++s) { v2u pk[2];
; #pragma unroll
;               for (int half = 0; half < 2; ++half) { const int ch0 = 16 * s + 8 * half;
;                   const f32x4 hin = *(const LAS f32x4*)(hp + ch0); const v2u graw = graw_[s * 2 + half];
;                   const float g0 = bflo(graw.x), g1 = bfhi(graw.x), g2 = bflo(graw.y), g3 = bfhi(graw.y);
;                   const float y0 = (xc[s][half][0] + Av[s][half][0] * hin[0]) * (g0 * sigmoid_(g0));
;                   const float y1 = (xc[s][half][1] + Av[s][half][1] * hin[1]) * (g1 * sigmoid_(g1));
;                   const float y2 = (xc[s][half][2] + Av[s][half][2] * hin[2]) * (g2 * sigmoid_(g2));
;                   const float y3 = (xc[s][half][3] + Av[s][half][3] * hin[3]) * (g3 * sigmoid_(g3));
;                   pk[half].x = pk2(y0, y1); pk[half].y = pk2(y2, y3); }
;               const auto rx = __builtin_amdgcn_permlane32_swap(pk[0].x, pk[1].x, false, false), ry = __builtin_amdgcn_permlane32_swap(pk[0].y, pk[1].y, false, false);
;               const v4u o = {rx[0], ry[0], rx[1], ry[1]};
;               *(v4u*)(yp + 16 * s) = o; __builtin_amdgcn_sched_barrier(0); } }
	v_pk_fma_f32 v[44:45], v[60:61], v[44:45], v[64:65]
	v_pk_mul_f32 v[52:53], v[54:55], v[52:53]
	v_pk_fma_f32 v[46:47], v[62:63], v[46:47], v[66:67]
	v_pk_mul_f32 v[44:45], v[52:53], v[44:45]
	v_pk_mul_f32 v[52:53], v[58:59], v[56:57]
	v_cvt_pk_bf16_f32 v44, v44, v45
	v_pk_mul_f32 v[46:47], v[52:53], v[46:47]
	v_lshlrev_b32_e32 v54, 16, v193
	v_cvt_pk_bf16_f32 v45, v46, v47
	v_lshlrev_b32_e32 v46, 16, v192
	v_mul_f32_e32 v47, 0xbfb8aa3b, v46
	v_exp_f32_e32 v52, v47
	v_and_b32_e32 v47, 0xffff0000, v192
	v_mul_f32_e32 v53, 0xbfb8aa3b, v47
	v_and_b32_e32 v55, 0xffff0000, v193
	v_exp_f32_e32 v53, v53
	v_mul_f32_e32 v56, 0xbfb8aa3b, v54
	v_mul_f32_e32 v57, 0xbfb8aa3b, v55
	v_exp_f32_e32 v56, v56
	v_exp_f32_e32 v57, v57
	v_add_f32_e32 v52, 1.0, v52
	v_add_f32_e32 v53, 1.0, v53
	v_rcp_f32_e32 v52, v52
	v_rcp_f32_e32 v53, v53
	v_add_f32_e32 v56, 1.0, v56
	v_add_f32_e32 v57, 1.0, v57
	v_rcp_f32_e32 v56, v56
	v_rcp_f32_e32 v57, v57
	s_waitcnt lgkmcnt(0)
	v_pk_fma_f32 v[48:49], v[68:69], v[48:49], v[72:73]
	v_pk_mul_f32 v[46:47], v[52:53], v[46:47]
	s_nop 0
	v_pk_mul_f32 v[46:47], v[46:47], v[48:49]
	v_pk_fma_f32 v[48:49], v[70:71], v[50:51], v[74:75]
	v_pk_mul_f32 v[50:51], v[56:57], v[54:55]
	v_cvt_pk_bf16_f32 v46, v46, v47
	v_pk_mul_f32 v[48:49], v[50:51], v[48:49]
	s_nop 0
	v_permlane32_swap_b32_e32 v44, v46
	v_cvt_pk_bf16_f32 v47, v48, v49
	s_nop 1
	v_permlane32_swap_b32_e32 v45, v47
	global_store_dwordx4 v[198:199], v[44:47], off offset:32
	v_lshlrev_b32_e32 v52, 16, v190
	v_mul_f32_e32 v53, 0xbfb8aa3b, v52
	v_exp_f32_e32 v54, v53
	v_and_b32_e32 v53, 0xffff0000, v190
	v_mul_f32_e32 v55, 0xbfb8aa3b, v53
	v_lshlrev_b32_e32 v56, 16, v191
	v_and_b32_e32 v57, 0xffff0000, v191
	v_exp_f32_e32 v55, v55
	v_mul_f32_e32 v58, 0xbfb8aa3b, v56
	v_mul_f32_e32 v59, 0xbfb8aa3b, v57
	v_exp_f32_e32 v58, v58
	v_exp_f32_e32 v59, v59
	v_add_f32_e32 v54, 1.0, v54
	v_add_f32_e32 v55, 1.0, v55
	ds_read_b128 v[44:47], v129 offset:44672
	ds_read_b128 v[48:51], v129 offset:44704
	v_rcp_f32_e32 v54, v54
	v_rcp_f32_e32 v55, v55
	v_add_f32_e32 v58, 1.0, v58
	v_add_f32_e32 v59, 1.0, v59
	v_rcp_f32_e32 v58, v58
	v_rcp_f32_e32 v59, v59
	s_waitcnt lgkmcnt(1)
	v_pk_fma_f32 v[44:45], v[80:81], v[44:45], v[84:85]
	v_pk_mul_f32 v[52:53], v[54:55], v[52:53]
	v_pk_fma_f32 v[46:47], v[82:83], v[46:47], v[86:87]
	v_pk_mul_f32 v[44:45], v[52:53], v[44:45]
	v_pk_mul_f32 v[52:53], v[58:59], v[56:57]
	v_cvt_pk_bf16_f32 v44, v44, v45
	v_pk_mul_f32 v[46:47], v[52:53], v[46:47]
	v_lshlrev_b32_e32 v54, 16, v189
	v_cvt_pk_bf16_f32 v45, v46, v47
	v_lshlrev_b32_e32 v46, 16, v188
	v_mul_f32_e32 v47, 0xbfb8aa3b, v46
	v_exp_f32_e32 v52, v47
	v_and_b32_e32 v47, 0xffff0000, v188
	v_mul_f32_e32 v53, 0xbfb8aa3b, v47
	v_and_b32_e32 v55, 0xffff0000, v189
	v_exp_f32_e32 v53, v53
	v_mul_f32_e32 v56, 0xbfb8aa3b, v54
	v_mul_f32_e32 v57, 0xbfb8aa3b, v55
	v_exp_f32_e32 v56, v56
	v_exp_f32_e32 v57, v57
	v_add_f32_e32 v52, 1.0, v52
	v_add_f32_e32 v53, 1.0, v53
	v_rcp_f32_e32 v52, v52
	v_rcp_f32_e32 v53, v53
	v_add_f32_e32 v56, 1.0, v56
	v_add_f32_e32 v57, 1.0, v57
	v_rcp_f32_e32 v56, v56
	v_rcp_f32_e32 v57, v57
	s_waitcnt lgkmcnt(0)
	v_pk_fma_f32 v[48:49], v[88:89], v[48:49], v[92:93]
	v_pk_mul_f32 v[46:47], v[52:53], v[46:47]
	s_nop 0
	v_pk_mul_f32 v[46:47], v[46:47], v[48:49]
	v_pk_fma_f32 v[48:49], v[90:91], v[50:51], v[94:95]
	v_pk_mul_f32 v[50:51], v[56:57], v[54:55]
	v_cvt_pk_bf16_f32 v46, v46, v47
	v_pk_mul_f32 v[48:49], v[50:51], v[48:49]
	s_nop 0
	v_permlane32_swap_b32_e32 v44, v46
	v_cvt_pk_bf16_f32 v47, v48, v49
	s_nop 1
	v_permlane32_swap_b32_e32 v45, v47
	global_store_dwordx4 v[198:199], v[44:47], off offset:64
	v_lshlrev_b32_e32 v52, 16, v182
	v_mul_f32_e32 v53, 0xbfb8aa3b, v52
	v_exp_f32_e32 v54, v53
	v_and_b32_e32 v53, 0xffff0000, v182
	v_mul_f32_e32 v55, 0xbfb8aa3b, v53
	v_lshlrev_b32_e32 v56, 16, v183
	v_and_b32_e32 v57, 0xffff0000, v183
	v_exp_f32_e32 v55, v55
	v_mul_f32_e32 v58, 0xbfb8aa3b, v56
	v_mul_f32_e32 v59, 0xbfb8aa3b, v57
	v_exp_f32_e32 v58, v58
	v_exp_f32_e32 v59, v59
	v_add_f32_e32 v54, 1.0, v54
	v_add_f32_e32 v55, 1.0, v55
	ds_read_b128 v[44:47], v129 offset:44736
	ds_read_b128 v[48:51], v129 offset:44768
	v_rcp_f32_e32 v54, v54
	v_rcp_f32_e32 v55, v55
	v_add_f32_e32 v58, 1.0, v58
	v_add_f32_e32 v59, 1.0, v59
	v_rcp_f32_e32 v58, v58
	v_rcp_f32_e32 v59, v59
	s_waitcnt lgkmcnt(1)
; #define LAS __attribute__((address_space(3)))
; __device__ __forceinline__ unsigned pk2(float lo, float hi) { f32x2_t v = {lo, hi}; bf16x2_t b = __builtin_convertvector(v, bf16x2_t); return __builtin_bit_cast(unsigned, b); }
; __device__ __forceinline__ float bflo(unsigned u) { return __uint_as_float(u << 16); }
; __device__ __forceinline__ float bfhi(unsigned u) { return __uint_as_float(u & 0xffff0000u); }
; __device__ __forceinline__ float sigmoid_(float x) { return rcpf_(1.0f + ex2(-LOG2E * x)); }
; __device__ __forceinline__ void lru_phase(const Ptrs& P, LAS unsigned char* lds, int G, int wave, int lane, int tid) {
;     ...
;           for (int s = 0; s < 5; ++s) { v2u pk[2];
; #pragma unroll
;               for (int half = 0; half < 2; ++half) { const int ch0 = 16 * s + 8 * half;
;                   const f32x4 hin = *(const LAS f32x4*)(hp + ch0); const v2u graw = graw_[s * 2 + half];
;                   const float g0 = bflo(graw.x), g1 = bfhi(graw.x), g2 = bflo(graw.y), g3 = bfhi(graw.y);
;                   const float y0 = (xc[s][half][0] + Av[s][half][0] * hin[0]) * (g0 * sigmoid_(g0));
;                   const float y1 = (xc[s][half][1] + Av[s][half][1] * hin[1]) * (g1 * sigmoid_(g1));
;                   const float y2 = (xc[s][half][2] + Av[s][half][2] * hin[2]) * (g2 * sigmoid_(g2));
;                   const float y3 = (xc[s][half][3] + Av[s][half][3] * hin[3]) * (g3 * sigmoid_(g3));
;                   pk[half].x = pk2(y0, y1); pk[half].y = pk2(y2, y3); }
;               const auto rx = __builtin_amdgcn_permlane32_swap(pk[0].x, pk[1].x, false, false), ry = __builtin_amdgcn_permlane32_swap(pk[0].y, pk[1].y, false, false);
;               const v4u o = {rx[0], ry[0], rx[1], ry[1]};
;               *(v4u*)(yp + 16 * s) = o; __builtin_amdgcn_sched_barrier(0); } }
;     }
;     __syncthreads();
	v_pk_fma_f32 v[44:45], v[96:97], v[44:45], v[100:101]
	v_pk_mul_f32 v[52:53], v[54:55], v[52:53]
	v_pk_fma_f32 v[46:47], v[98:99], v[46:47], v[102:103]
	v_pk_mul_f32 v[44:45], v[52:53], v[44:45]
	v_pk_mul_f32 v[52:53], v[58:59], v[56:57]
	v_cvt_pk_bf16_f32 v44, v44, v45
	v_pk_mul_f32 v[46:47], v[52:53], v[46:47]
	v_lshlrev_b32_e32 v54, 16, v181
	v_cvt_pk_bf16_f32 v45, v46, v47
	v_lshlrev_b32_e32 v46, 16, v180
	v_mul_f32_e32 v47, 0xbfb8aa3b, v46
	v_exp_f32_e32 v52, v47
	v_and_b32_e32 v47, 0xffff0000, v180
	v_mul_f32_e32 v53, 0xbfb8aa3b, v47
	v_and_b32_e32 v55, 0xffff0000, v181
	v_exp_f32_e32 v53, v53
	v_mul_f32_e32 v56, 0xbfb8aa3b, v54
	v_mul_f32_e32 v57, 0xbfb8aa3b, v55
	v_exp_f32_e32 v56, v56
	v_exp_f32_e32 v57, v57
	v_add_f32_e32 v52, 1.0, v52
	v_add_f32_e32 v53, 1.0, v53
	v_rcp_f32_e32 v52, v52
	v_rcp_f32_e32 v53, v53
	v_add_f32_e32 v56, 1.0, v56
	v_add_f32_e32 v57, 1.0, v57
	v_rcp_f32_e32 v56, v56
	v_rcp_f32_e32 v57, v57
	s_waitcnt lgkmcnt(0)
	v_pk_fma_f32 v[48:49], v[104:105], v[48:49], v[108:109]
	v_pk_mul_f32 v[46:47], v[52:53], v[46:47]
	s_nop 0
	v_pk_mul_f32 v[46:47], v[46:47], v[48:49]
	v_pk_fma_f32 v[48:49], v[106:107], v[50:51], v[110:111]
	v_pk_mul_f32 v[50:51], v[56:57], v[54:55]
	v_cvt_pk_bf16_f32 v46, v46, v47
	v_pk_mul_f32 v[48:49], v[50:51], v[48:49]
	s_nop 0
	v_permlane32_swap_b32_e32 v44, v46
	v_cvt_pk_bf16_f32 v47, v48, v49
	s_nop 1
	v_permlane32_swap_b32_e32 v45, v47
	global_store_dwordx4 v[198:199], v[44:47], off offset:96
	v_lshlrev_b32_e32 v52, 16, v178
	v_mul_f32_e32 v53, 0xbfb8aa3b, v52
	v_exp_f32_e32 v54, v53
	v_and_b32_e32 v53, 0xffff0000, v178
	ds_read_b128 v[44:47], v129 offset:44800
	ds_read_b128 v[48:51], v129 offset:44832
	v_mul_f32_e32 v55, 0xbfb8aa3b, v53
	v_exp_f32_e32 v55, v55
	v_add_f32_e32 v54, 1.0, v54
	s_waitcnt lgkmcnt(1)
	v_pk_fma_f32 v[0:1], v[0:1], v[44:45], v[8:9]
	v_lshlrev_b32_e32 v8, 16, v179
	v_and_b32_e32 v9, 0xffff0000, v179
	v_add_f32_e32 v44, 1.0, v55
	v_mul_f32_e32 v45, 0xbfb8aa3b, v8
	v_mul_f32_e32 v55, 0xbfb8aa3b, v9
	v_exp_f32_e32 v45, v45
	v_exp_f32_e32 v56, v55
	v_rcp_f32_e32 v55, v44
	v_rcp_f32_e32 v54, v54
	v_add_f32_e32 v44, 1.0, v45
	v_add_f32_e32 v45, 1.0, v56
	v_rcp_f32_e32 v44, v44
	v_rcp_f32_e32 v45, v45
	v_pk_mul_f32 v[52:53], v[54:55], v[52:53]
	v_pk_fma_f32 v[2:3], v[2:3], v[46:47], v[10:11]
	v_pk_mul_f32 v[0:1], v[52:53], v[0:1]
	v_pk_mul_f32 v[8:9], v[44:45], v[8:9]
	v_cvt_pk_bf16_f32 v0, v0, v1
	v_pk_mul_f32 v[2:3], v[8:9], v[2:3]
	v_lshlrev_b32_e32 v10, 16, v177
	v_cvt_pk_bf16_f32 v1, v2, v3
	v_lshlrev_b32_e32 v2, 16, v176
	v_mul_f32_e32 v3, 0xbfb8aa3b, v2
	v_exp_f32_e32 v8, v3
	v_and_b32_e32 v3, 0xffff0000, v176
	v_mul_f32_e32 v9, 0xbfb8aa3b, v3
	v_and_b32_e32 v11, 0xffff0000, v177
	v_exp_f32_e32 v9, v9
	s_waitcnt lgkmcnt(0)
	v_pk_fma_f32 v[4:5], v[4:5], v[48:49], v[12:13]
	v_mul_f32_e32 v12, 0xbfb8aa3b, v10
	v_mul_f32_e32 v13, 0xbfb8aa3b, v11
	v_exp_f32_e32 v12, v12
	v_exp_f32_e32 v13, v13
	v_add_f32_e32 v8, 1.0, v8
	v_add_f32_e32 v9, 1.0, v9
	v_rcp_f32_e32 v8, v8
	v_rcp_f32_e32 v9, v9
	v_add_f32_e32 v12, 1.0, v12
	v_add_f32_e32 v13, 1.0, v13
	v_rcp_f32_e32 v12, v12
	v_rcp_f32_e32 v13, v13
	v_pk_mul_f32 v[2:3], v[8:9], v[2:3]
	s_nop 0
	v_pk_mul_f32 v[2:3], v[2:3], v[4:5]
	v_pk_fma_f32 v[4:5], v[6:7], v[50:51], v[14:15]
	v_pk_mul_f32 v[6:7], v[12:13], v[10:11]
	v_cvt_pk_bf16_f32 v2, v2, v3
	v_pk_mul_f32 v[4:5], v[6:7], v[4:5]
	s_nop 0
	v_permlane32_swap_b32_e32 v0, v2
	v_cvt_pk_bf16_f32 v3, v4, v5
	s_nop 1
	v_permlane32_swap_b32_e32 v1, v3
	global_store_dwordx4 v[198:199], v[0:3], off offset:128
	s_andn2_b64 vcc, exec, s[18:19]
	s_mov_b32 s20, s36
	s_cbranch_vccz .LBB0_326

; #define LAS __attribute__((address_space(3)))
; __device__ __forceinline__ void lru_phase(const Ptrs& P, LAS unsigned char* lds, int G, int wave, int lane, int tid) {
;     ...
;         { const int un = u + G < 64 * NCHUNK ? u + G : u; LRU_LOAD_RAW(un); }
;         unsigned long long gv_early = 0ull;
;         if (tid < LB && c > 0) gv_early = __hip_atomic_load(GR + ((size_t)bh * NCHUNK + (c - 1)) * LB + tid, __ATOMIC_RELAXED, __HIP_MEMORY_SCOPE_AGENT);
;         __syncthreads();
;         if (tid < LB) { const LAS float* cp = (const LAS float*)(lds + L_COMP) + tid;
;             float Au = 1.0f, Bu = 0.0f;
; #pragma unroll
;             for (int w = 0; w < 8; ++w) { const float a = cp[w * 160], bb = cp[w * 160 + 80]; Bu = a * Bu + bb; Au = Au * a; }
;             float h = 0.0f;
;             if (c > 0) { unsigned long long* src = GR + ((size_t)bh * NCHUNK + (c - 1)) * LB + tid; unsigned long long v = gv_early; unsigned sp = 0;
;                 while ((unsigned)(v >> 32) != 1u && ++sp <= (1u << 22)) { __builtin_amdgcn_s_sleep(1); v = __hip_atomic_load(src, __ATOMIC_RELAXED, __HIP_MEMORY_SCOPE_AGENT); }
;                 h = __uint_as_float((unsigned)v); }
;             __hip_atomic_store(GR + ((size_t)bh * NCHUNK + c) * LB + tid, (1ull << 32) | (unsigned long long)__float_as_uint(Au * h + Bu), __ATOMIC_RELAXED, __HIP_MEMORY_SCOPE_AGENT);
;             LAS float* hp = (LAS float*)(lds + L_HIN) + tid;
; #pragma unroll
;             for (int w = 0; w < 8; ++w) { hp[w * 80] = h; h = cp[w * 160] * h + cp[w * 160 + 80]; } }
.LBB0_318:
	s_or_b64 exec, exec, s[6:7]
	global_load_dwordx2 v[162:163], v[26:27], off offset:1024
	global_load_dwordx2 v[158:159], v[26:27], off offset:1536
	global_load_dwordx2 v[152:153], v[26:27], off offset:2048
	global_load_dwordx2 v[146:147], v[26:27], off offset:2560
	global_load_dwordx2 v[140:141], v[26:27], off offset:3072
	global_load_dwordx2 v[122:123], v[26:27], off offset:3584
	v_add_co_u32_e32 v198, vcc, 0x1000, v26
	s_and_b32 s22, s20, 63
	s_nop 0
	v_addc_co_u32_e32 v199, vcc, 0, v27, vcc
	global_load_dwordx2 v[174:175], v[26:27], off
	global_load_dwordx2 v[170:171], v[26:27], off offset:512
	global_load_dwordx2 v[120:121], v[198:199], off
	s_nop 0
	global_load_dwordx2 v[26:27], v[198:199], off offset:512
	s_cmp_gt_i32 s35, 3
	s_cselect_b64 s[6:7], -1, 0
	s_and_b64 s[24:25], s[4:5], s[6:7]
	v_mov_b64_e32 v[204:205], 0
	s_and_saveexec_b64 s[20:21], s[24:25]
	s_cbranch_execz .LBB0_320
	s_lshl_b32 s23, s22, 4
	s_and_b32 s39, s35, -4
	s_add_i32 s23, s39, s23
	s_add_i32 s23, s23, -1
	v_mad_u64_u32 v[198:199], s[24:25], s23, v239, v[132:133]
	global_load_dwordx2 v[204:205], v[198:199], off sc1
.LBB0_320:
	s_or_b64 exec, exec, s[20:21]
	s_waitcnt lgkmcnt(0)
	s_barrier
	s_and_saveexec_b64 s[20:21], s[4:5]
	s_cbranch_execz .LBB0_307
	v_add_u32_e32 v139, 0x9a00, v236
	ds_read2_b32 v[198:199], v139 offset1:80
	ds_read2_b32 v[202:203], v139 offset0:160 offset1:240
	v_add_u32_e32 v221, 0x500, v139
	ds_read2_b32 v[206:207], v221 offset1:80
	ds_read2_b32 v[208:209], v221 offset0:160 offset1:240
	v_add_u32_e32 v223, 0xa00, v139
	ds_read2_b32 v[210:211], v223 offset1:80
	ds_read2_b32 v[212:213], v223 offset0:160 offset1:240
	v_add_u32_e32 v225, 0xf00, v139
	ds_read2_b32 v[214:215], v225 offset1:80
	ds_read2_b32 v[216:217], v225 offset0:160 offset1:240
	s_waitcnt lgkmcnt(0)
	v_fma_f32 v218, 0, v198, v199
	v_fma_f32 v218, v218, v202, v203
	v_fma_f32 v218, v218, v206, v207
	v_fma_f32 v218, v218, v208, v209
	v_fma_f32 v218, v218, v210, v211
	v_fma_f32 v218, v218, v212, v213
	v_fma_f32 v218, v218, v214, v215
	v_mov_b32_e32 v219, v217
	v_fmac_f32_e32 v219, v218, v216
	v_mul_f32_e32 v220, v198, v202
	v_mul_f32_e32 v220, v220, v206
	v_mul_f32_e32 v220, v220, v208
	v_mul_f32_e32 v220, v220, v210
	v_mul_f32_e32 v220, v220, v212
	v_mul_f32_e32 v220, v220, v214
	v_mul_f32_e32 v220, v220, v216
	s_and_b32 s68, s35, 3
	s_cmp_eq_u32 s68, 3
	s_cbranch_scc1 .Lp2_nopub
	s_lshr_b32 s69, s35, 2
	s_mul_i32 s69, s69, 3
	s_add_i32 s69, s69, s68
	s_mul_i32 s70, s22, 12
	s_add_i32 s69, s69, s70
	s_mul_i32 s69, s69, 0x500
	s_add_u32 s72, s54, s69
	s_addc_u32 s73, s55, 0
	s_add_u32 s72, s72, 0x1300000
	s_addc_u32 s73, s73, 0
	v_mov_b32_e32 v252, v220
	v_mov_b32_e32 v253, 1
	v_mov_b32_e32 v254, v219
	v_mov_b32_e32 v255, 1
	global_store_dwordx4 v186, v[252:255], s[72:73] sc1
.Lp2_nopub:
	v_mov_b32_e32 v250, 0
	s_and_b32 s69, s35, -4
	s_cmp_eq_u32 s69, 0
	s_cbranch_scc1 .Lp2_lb_loop_init
	s_lshl_b32 s70, s22, 4
	s_add_i32 s70, s70, s69
	s_add_i32 s70, s70, -1
	v_mad_u64_u32 v[222:223], s[74:75], s70, v239, v[132:133]
	s_mov_b32 s76, 0
.Lp2_lb_g:
	s_waitcnt vmcnt(0)
	v_cmp_ne_u32_e32 vcc, 1, v205
	s_cbranch_vccz .Lp2_lb_g_ok
	s_add_i32 s76, s76, 1
	s_cmp_gt_u32 s76, 0x20000
	s_cbranch_scc1 .Lp2_lb_g_ok
	s_sleep 1
	global_load_dwordx2 v[204:205], v[222:223], off sc1
	s_branch .Lp2_lb_g
.Lp2_lb_g_ok:
	v_mov_b32_e32 v250, v204
.Lp2_lb_loop_init:
	s_mov_b32 s77, s69
.Lp2_lb_j:
	s_cmp_ge_u32 s77, s35
	s_cbranch_scc1 .Lp2_lb_done
	s_lshr_b32 s70, s77, 2
	s_mul_i32 s70, s70, 3
	s_and_b32 s71, s77, 3
	s_add_i32 s70, s70, s71
	s_mul_i32 s71, s22, 12
	s_add_i32 s70, s70, s71
	s_mul_i32 s70, s70, 0x500
	s_add_u32 s78, s54, s70
	s_addc_u32 s79, s55, 0
	s_add_u32 s78, s78, 0x1300000
	s_addc_u32 s79, s79, 0
	s_mov_b32 s76, 0
.Lp2_lb_cd:
	global_load_dwordx4 v[252:255], v186, s[78:79] sc1
	s_waitcnt vmcnt(0)
	v_cmp_ne_u32_e32 vcc, 1, v253
	v_cmp_ne_u32_e64 s[74:75], 1, v255
	s_or_b64 vcc, vcc, s[74:75]
	s_cbranch_vccz .Lp2_lb_cd_ok
	s_add_i32 s76, s76, 1
	s_cmp_gt_u32 s76, 0x20000
	s_cbranch_scc1 .Lp2_lb_cd_ok
	s_sleep 1
	s_branch .Lp2_lb_cd
.Lp2_lb_cd_ok:
	v_fmac_f32_e32 v254, v252, v250
	v_mov_b32_e32 v250, v254
	s_add_i32 s77, s77, 1
	s_branch .Lp2_lb_j
.Lp2_lb_done:
	v_mov_b32_e32 v136, v219
	v_fmac_f32_e32 v136, v220, v250
	s_lshl_b32 s70, s22, 4
	s_add_i32 s70, s70, s35
	v_mad_u64_u32 v[222:223], s[74:75], s70, v239, v[132:133]
	global_store_dwordx2 v[222:223], v[136:137], off sc1
	v_fmac_f32_e32 v199, v198, v250
	v_fmac_f32_e32 v203, v199, v202
	v_fmac_f32_e32 v207, v203, v206
	v_fmac_f32_e32 v209, v207, v208
	v_fmac_f32_e32 v211, v209, v210
	v_fmac_f32_e32 v213, v211, v212
	v_fmac_f32_e32 v215, v213, v214
	v_add_u32_e32 v139, 0xae00, v236
	ds_write2_b32 v139, v250, v199 offset1:80
	ds_write2_b32 v139, v203, v207 offset0:160 offset1:240
	v_add_u32_e32 v139, 0x500, v139
	ds_write2_b32 v139, v209, v211 offset1:80
	ds_write2_b32 v139, v213, v215 offset0:160 offset1:240
	s_branch .LBB0_307
